# v22 + bf16 norm loop: per-row wave reduction via DPP quad/mirror adds and permlane16/32 swaps instead of six dependent ds_bpermute round trips (bit-identical)
# baseline (speedup 1.0000x reference)
; __device__ __forceinline__ float bflo(unsigned v) { return __uint_as_float(v << 16); }
; __device__ __forceinline__ float bfhi(unsigned v) { return __uint_as_float(v & 0xffff0000u); }
; __device__ __forceinline__ unsigned pk2(float lo, float hi) { return pg8::cvt_pk_bf16(lo, hi); }
; __device__ __forceinline__ void norm_phase_b(Frame& F0, const bf16* xin, const float* g, const float* modl, int j, bf16* outb) {
;     ...
;     for (int m = gw; m < M; m += NGW) {
;         const int b = m >> 13;
;         const u32x4 ra = *(const u32x4*)(xin + (size_t)m * D + F.lane * 16), rb = *(const u32x4*)(xin + (size_t)m * D + F.lane * 16 + 8);
;         const float* sh = modl + (size_t)b * 9216 + (j * 3 + 0) * D + F.lane * 16; const float* sc = modl + (size_t)b * 9216 + (j * 3 + 1) * D + F.lane * 16; const float* gg = g + F.lane * 16;
;         float xv[16];
;         xv[0] = bflo(ra.x); xv[1] = bfhi(ra.x); xv[2] = bflo(ra.y); xv[3] = bfhi(ra.y); xv[4] = bflo(ra.z); xv[5] = bfhi(ra.z); xv[6] = bflo(ra.w); xv[7] = bfhi(ra.w);
;         xv[8] = bflo(rb.x); xv[9] = bfhi(rb.x); xv[10] = bflo(rb.y); xv[11] = bfhi(rb.y); xv[12] = bflo(rb.z); xv[13] = bfhi(rb.z); xv[14] = bflo(rb.w); xv[15] = bfhi(rb.w);
;         float s = 0.f;
; #pragma unroll
;         for (int e = 0; e < 16; ++e) s += xv[e] * xv[e];
;         const float rstd = rsqrtf(wave_sum(s) * (1.f / D) + EPS);
; #pragma unroll
;         for (int e4 = 0; e4 < 4; ++e4) { const f32x4 gv = *(const f32x4*)(gg + 4 * e4), sv = *(const f32x4*)(sc + 4 * e4), hv = *(const f32x4*)(sh + 4 * e4);
;             xv[4 * e4] = xv[4 * e4] * rstd * gv.x * (sv.x + 1.0f) + hv.x; xv[4 * e4 + 1] = xv[4 * e4 + 1] * rstd * gv.y * (sv.y + 1.0f) + hv.y;
;             xv[4 * e4 + 2] = xv[4 * e4 + 2] * rstd * gv.z * (sv.z + 1.0f) + hv.z; xv[4 * e4 + 3] = xv[4 * e4 + 3] * rstd * gv.w * (sv.w + 1.0f) + hv.w; }
;         u32x4 oa, ob; oa.x = pk2(xv[0], xv[1]); oa.y = pk2(xv[2], xv[3]); oa.z = pk2(xv[4], xv[5]); oa.w = pk2(xv[6], xv[7]);
;         ob.x = pk2(xv[8], xv[9]); ob.y = pk2(xv[10], xv[11]); ob.z = pk2(xv[12], xv[13]); ob.w = pk2(xv[14], xv[15]);
;         *(u32x4*)(outb + (size_t)m * D + F.lane * 16) = oa; *(u32x4*)(outb + (size_t)m * D + F.lane * 16 + 8) = ob;
;     }
.LBB0_304:
	s_ashr_i32 s5, s0, 13
	v_lshl_add_u64 v[22:23], s[56:57], 0, v[20:21]
	global_load_dwordx4 v[2:5], v[18:19], off offset:48
	global_load_dwordx4 v[6:9], v[18:19], off offset:32
	global_load_dwordx4 v[10:13], v[18:19], off offset:16
	global_load_dwordx4 v[14:17], v[18:19], off
	global_load_dwordx4 v[30:33], v[22:23], off
	global_load_dwordx4 v[34:37], v[22:23], off offset:-16
	s_mul_hi_i32 s7, s5, 0x9000
	s_mul_i32 s5, s5, 0x9000
	v_lshl_add_u64 v[38:39], s[76:77], 0, v[20:21]
	s_add_u32 s6, s1, s5
	v_add_co_u32_e32 v22, vcc, 0x7e00000, v38
	s_addc_u32 s7, s4, s7
	s_nop 0
	v_addc_co_u32_e32 v23, vcc, 0, v39, vcc
	v_lshl_add_u64 v[54:55], s[6:7], 0, v[0:1]
	v_add_co_u32_e32 v66, vcc, s59, v54
	v_lshl_add_u64 v[62:63], v[54:55], 0, s[68:69]
	s_nop 0
	v_addc_co_u32_e32 v67, vcc, 0, v55, vcc
	global_load_dwordx4 v[38:41], v0, s[6:7] offset:16
	global_load_dwordx4 v[42:45], v0, s[6:7]
	global_load_dwordx4 v[46:49], v0, s[6:7] offset:32
	global_load_dwordx4 v[50:53], v0, s[6:7] offset:48
	global_load_dwordx4 v[54:57], v[62:63], off offset:32
	global_load_dwordx4 v[58:61], v[62:63], off offset:16
	s_nop 0
	global_load_dwordx4 v[62:65], v[62:63], off offset:48
	s_nop 0
	global_load_dwordx4 v[66:69], v[66:67], off
	s_add_i32 s0, s0, s64
	v_lshl_add_u64 v[20:21], v[20:21], 0, s[52:53]
	s_cmp_lt_i32 s0, 0x8000
	s_waitcnt vmcnt(0)
	v_lshlrev_b32_e32 v70, 16, v33
	v_lshlrev_b32_e32 v78, 16, v34
	v_and_b32_e32 v79, 0xffff0000, v34
	v_and_b32_e32 v71, 0xffff0000, v33
	v_lshlrev_b32_e32 v72, 16, v32
	v_and_b32_e32 v73, 0xffff0000, v32
	v_lshlrev_b32_e32 v32, 16, v31
	v_and_b32_e32 v33, 0xffff0000, v31
	v_lshlrev_b32_e32 v74, 16, v30
	v_and_b32_e32 v75, 0xffff0000, v30
	v_lshlrev_b32_e32 v30, 16, v37
	v_and_b32_e32 v31, 0xffff0000, v37
	v_lshlrev_b32_e32 v76, 16, v36
	v_and_b32_e32 v77, 0xffff0000, v36
	v_lshlrev_b32_e32 v36, 16, v35
	v_and_b32_e32 v37, 0xffff0000, v35
	v_pk_mul_f32 v[34:35], v[78:79], v[78:79]
	v_pk_mul_f32 v[80:81], v[36:37], v[36:37]
	v_add_f32_e32 v34, v34, v35
	v_add_f32_e32 v34, v80, v34
	v_pk_mul_f32 v[82:83], v[76:77], v[76:77]
	v_add_f32_e32 v80, v81, v34
	v_add_f32_e32 v80, v82, v80
	v_pk_mul_f32 v[84:85], v[30:31], v[30:31]
	v_pk_add_f32 v[34:35], v[56:57], 1.0 op_sel_hi:[1,0]
	v_pk_add_f32 v[56:57], v[60:61], 1.0 op_sel_hi:[1,0]
	v_pk_add_f32 v[60:61], v[62:63], 1.0 op_sel_hi:[1,0]
	v_pk_add_f32 v[62:63], v[64:65], 1.0 op_sel_hi:[1,0]
	v_pk_add_f32 v[64:65], v[68:69], 1.0 op_sel_hi:[1,0]
	v_add_f32_e32 v68, v83, v80
	v_add_f32_e32 v68, v84, v68
	v_pk_mul_f32 v[86:87], v[74:75], v[74:75]
	v_add_f32_e32 v68, v85, v68
	v_add_f32_e32 v68, v86, v68
	v_pk_mul_f32 v[88:89], v[32:33], v[32:33]
	v_add_f32_e32 v68, v87, v68
	v_add_f32_e32 v68, v88, v68
	v_pk_mul_f32 v[90:91], v[72:73], v[72:73]
	v_add_f32_e32 v68, v89, v68
	v_add_f32_e32 v68, v90, v68
	v_pk_mul_f32 v[92:93], v[70:71], v[70:71]
	v_add_f32_e32 v68, v91, v68
	v_add_f32_e32 v68, v92, v68
	v_add_f32_e32 v68, v93, v68
	v_pk_add_f32 v[58:59], v[58:59], 1.0 op_sel_hi:[1,0]
	v_pk_add_f32 v[66:67], v[66:67], 1.0 op_sel_hi:[1,0]
	v_pk_add_f32 v[54:55], v[54:55], 1.0 op_sel_hi:[1,0]
	v_add_f32_dpp v68, v68, v68 quad_perm:[1,0,3,2] row_mask:0xf bank_mask:0xf
	s_nop 1
	v_add_f32_dpp v68, v68, v68 quad_perm:[2,3,0,1] row_mask:0xf bank_mask:0xf
	s_nop 1
	v_add_f32_dpp v68, v68, v68 row_half_mirror row_mask:0xf bank_mask:0xf
	s_nop 1
	v_add_f32_dpp v68, v68, v68 row_mirror row_mask:0xf bank_mask:0xf
	v_mov_b32_e32 v80, v68
	v_mov_b32_e32 v81, v68
	s_nop 1
	v_permlane16_swap_b32_e32 v80, v81
	v_add_f32_e32 v68, v80, v81
	v_mov_b32_e32 v80, v68
	v_mov_b32_e32 v81, v68
	s_nop 1
	v_permlane32_swap_b32_e32 v80, v81
	v_add_f32_e32 v68, v80, v81
	v_fmamk_f32 v68, v68, 0x3a800000, v183
	v_mul_f32_e32 v69, 0x4b800000, v68
	v_cmp_gt_f32_e32 vcc, s10, v68
	s_nop 1
	v_cndmask_b32_e32 v68, v68, v69, vcc
	v_rsq_f32_e32 v68, v68
	s_nop 0
	v_mul_f32_e32 v69, 0x45800000, v68
	v_cndmask_b32_e32 v68, v68, v69, vcc
	v_pk_mul_f32 v[78:79], v[68:69], v[78:79] op_sel_hi:[0,1]
	v_pk_mul_f32 v[36:37], v[68:69], v[36:37] op_sel_hi:[0,1]
	v_pk_mul_f32 v[76:77], v[68:69], v[76:77] op_sel_hi:[0,1]
	v_pk_mul_f32 v[30:31], v[68:69], v[30:31] op_sel_hi:[0,1]
	v_pk_mul_f32 v[74:75], v[68:69], v[74:75] op_sel_hi:[0,1]
	v_pk_mul_f32 v[32:33], v[68:69], v[32:33] op_sel_hi:[0,1]
	v_pk_mul_f32 v[72:73], v[68:69], v[72:73] op_sel_hi:[0,1]
	v_pk_mul_f32 v[68:69], v[68:69], v[70:71] op_sel_hi:[0,1]
	v_pk_mul_f32 v[14:15], v[14:15], v[78:79]
	v_pk_mul_f32 v[16:17], v[16:17], v[36:37]
	v_pk_mul_f32 v[10:11], v[10:11], v[76:77]
	v_pk_mul_f32 v[12:13], v[12:13], v[30:31]
	v_pk_mul_f32 v[6:7], v[6:7], v[74:75]
	v_pk_mul_f32 v[8:9], v[8:9], v[32:33]
	v_pk_mul_f32 v[2:3], v[2:3], v[72:73]
	v_pk_mul_f32 v[4:5], v[4:5], v[68:69]
	v_pk_fma_f32 v[14:15], v[66:67], v[14:15], v[42:43]
	v_pk_fma_f32 v[16:17], v[64:65], v[16:17], v[44:45]
	v_pk_fma_f32 v[10:11], v[58:59], v[10:11], v[38:39]
	v_pk_fma_f32 v[12:13], v[56:57], v[12:13], v[40:41]
	v_pk_fma_f32 v[6:7], v[54:55], v[6:7], v[46:47]
	v_pk_fma_f32 v[8:9], v[34:35], v[8:9], v[48:49]
	v_pk_fma_f32 v[30:31], v[60:61], v[2:3], v[50:51]
	v_pk_fma_f32 v[32:33], v[62:63], v[4:5], v[52:53]
	v_cvt_pk_bf16_f32 v2, v14, v15
	v_cvt_pk_bf16_f32 v3, v16, v17
	v_cvt_pk_bf16_f32 v4, v10, v11
	v_cvt_pk_bf16_f32 v5, v12, v13
	v_cvt_pk_bf16_f32 v6, v6, v7
	v_cvt_pk_bf16_f32 v7, v8, v9
	v_cvt_pk_bf16_f32 v8, v30, v31
	v_cvt_pk_bf16_f32 v9, v32, v33
	global_store_dwordx4 v[22:23], v[2:5], off
	global_store_dwordx4 v[22:23], v[6:9], off offset:16
	s_cbranch_scc1 .LBB0_304
